# FFN-down context K-slice f32 partial stores merged with v_permlane32_swap into 64-byte contiguous row pieces (half the write requests)
# speedup vs baseline: 1.0067x; 1.0022x over previous
.LBB0_1365:
	s_add_i32 s46, s14, 2
	s_add_u32 s12, s10, 0x100
	s_addc_u32 s13, s11, 0
	s_add_i32 s47, 0, 0x10000
	v_add_u32_e32 v134, s47, v230
	ds_read_b128 v[106:109], v134
	ds_read_b128 v[110:113], v134 offset:1024
	ds_read_b128 v[114:117], v134 offset:2048
	ds_read_b128 v[134:137], v134 offset:3072
	s_cmp_eq_u32 s43, s14
	s_cselect_b32 s14, s8, s44
	s_cselect_b32 s17, s7, s13
	s_cselect_b32 s16, s6, s12
	s_cselect_b32 s15, s9, s45
	v_lshl_add_u64 v[178:179], s[10:11], 0, v[184:185]
	s_add_i32 m0, s24, 0xc000
	ds_read_b128 v[138:141], v232
	ds_read_b128 v[150:153], v232 offset:1024
	ds_read_b128 v[154:157], v232 offset:2048
	ds_read_b128 v[158:161], v232 offset:3072
	ds_read_b128 v[162:165], v232 offset:4096
	ds_read_b128 v[166:169], v232 offset:5120
	ds_read_b128 v[170:173], v232 offset:6144
	ds_read_b128 v[174:177], v232 offset:7168
	global_load_lds_dwordx4 v[178:179], off
	v_lshl_add_u64 v[178:179], s[10:11], 0, v[186:187]
	s_add_i32 m0, s24, 0xe000
	s_nop 0
	global_load_lds_dwordx4 v[178:179], off
	s_waitcnt lgkmcnt(8)
	s_barrier
	s_waitcnt lgkmcnt(0)
	s_setprio 1
	s_waitcnt lgkmcnt(0)
	v_mfma_f32_16x16x32_f16 v[146:149], v[106:109], v[138:141], v[146:149]
	v_mfma_f32_16x16x32_f16 v[142:145], v[114:117], v[138:141], v[142:145]
	v_mfma_f32_16x16x32_f16 v[130:133], v[106:109], v[154:157], v[130:133]
	v_mfma_f32_16x16x32_f16 v[122:125], v[114:117], v[154:157], v[122:125]
	v_mfma_f32_16x16x32_f16 v[94:97], v[106:109], v[162:165], v[94:97]
	v_mfma_f32_16x16x32_f16 v[90:93], v[114:117], v[162:165], v[90:93]
	v_mfma_f32_16x16x32_f16 v[78:81], v[106:109], v[170:173], v[78:81]
	v_mfma_f32_16x16x32_f16 v[74:77], v[114:117], v[170:173], v[74:77]
	v_mfma_f32_16x16x32_f16 v[146:149], v[110:113], v[150:153], v[146:149]
	v_mfma_f32_16x16x32_f16 v[142:145], v[134:137], v[150:153], v[142:145]
	v_mfma_f32_16x16x32_f16 v[130:133], v[110:113], v[158:161], v[130:133]
	v_mfma_f32_16x16x32_f16 v[122:125], v[134:137], v[158:161], v[122:125]
	v_mfma_f32_16x16x32_f16 v[94:97], v[110:113], v[166:169], v[94:97]
	v_mfma_f32_16x16x32_f16 v[90:93], v[134:137], v[166:169], v[90:93]
	v_mfma_f32_16x16x32_f16 v[78:81], v[110:113], v[174:177], v[78:81]
	v_mfma_f32_16x16x32_f16 v[74:77], v[134:137], v[174:177], v[74:77]
	s_setprio 0
	s_barrier
	s_add_i32 s48, 0, 0x14000
	s_add_i32 s10, s47, s23
	v_add_u32_e32 v196, s48, v230
	v_lshl_add_u64 v[200:201], s[14:15], 0, v[32:33]
	s_mov_b32 m0, s10
	ds_read_b128 v[178:181], v196
	ds_read_b128 v[188:191], v196 offset:1024
	ds_read_b128 v[192:195], v196 offset:2048
	ds_read_b128 v[196:199], v196 offset:3072
	global_load_lds_dwordx4 v[200:201], off
	v_lshl_add_u64 v[202:203], s[14:15], 0, v[182:183]
	s_add_i32 m0, s10, 0x2000
	s_nop 0
	global_load_lds_dwordx4 v[202:203], off
	s_barrier
	s_waitcnt lgkmcnt(0)
	s_setprio 1
	s_waitcnt lgkmcnt(0)
	v_mfma_f32_16x16x32_f16 v[126:129], v[178:181], v[138:141], v[126:129]
	v_mfma_f32_16x16x32_f16 v[118:121], v[192:195], v[138:141], v[118:121]
	v_mfma_f32_16x16x32_f16 v[102:105], v[178:181], v[154:157], v[102:105]
	v_mfma_f32_16x16x32_f16 v[98:101], v[192:195], v[154:157], v[98:101]
	v_mfma_f32_16x16x32_f16 v[86:89], v[178:181], v[162:165], v[86:89]
	v_mfma_f32_16x16x32_f16 v[82:85], v[192:195], v[162:165], v[82:85]
	v_mfma_f32_16x16x32_f16 v[70:73], v[178:181], v[170:173], v[70:73]
	v_mfma_f32_16x16x32_f16 v[66:69], v[192:195], v[170:173], v[66:69]
	v_mfma_f32_16x16x32_f16 v[126:129], v[188:191], v[150:153], v[126:129]
	v_mfma_f32_16x16x32_f16 v[118:121], v[196:199], v[150:153], v[118:121]
	v_mfma_f32_16x16x32_f16 v[102:105], v[188:191], v[158:161], v[102:105]
	v_mfma_f32_16x16x32_f16 v[98:101], v[196:199], v[158:161], v[98:101]
	v_mfma_f32_16x16x32_f16 v[86:89], v[188:191], v[166:169], v[86:89]
	v_mfma_f32_16x16x32_f16 v[82:85], v[196:199], v[166:169], v[82:85]
	v_mfma_f32_16x16x32_f16 v[70:73], v[188:191], v[174:177], v[70:73]
	v_mfma_f32_16x16x32_f16 v[66:69], v[196:199], v[174:177], v[66:69]
	s_setprio 0
	s_mov_b32 m0, s24
	v_lshl_add_u64 v[204:205], s[16:17], 0, v[32:33]
	s_barrier
	ds_read_b128 v[138:141], v232 offset:16384
	ds_read_b128 v[150:153], v232 offset:17408
	ds_read_b128 v[154:157], v232 offset:18432
	ds_read_b128 v[158:161], v232 offset:19456
	ds_read_b128 v[162:165], v232 offset:20480
	ds_read_b128 v[166:169], v232 offset:21504
	ds_read_b128 v[170:173], v232 offset:22528
	ds_read_b128 v[174:177], v232 offset:23552
	global_load_lds_dwordx4 v[204:205], off
	v_lshl_add_u64 v[206:207], s[16:17], 0, v[182:183]
	s_mov_b32 m0, s25
	s_nop 0
	global_load_lds_dwordx4 v[206:207], off
	s_barrier
	s_waitcnt lgkmcnt(0)
	s_setprio 1
	s_waitcnt lgkmcnt(0)
	v_mfma_f32_16x16x32_f16 v[62:65], v[106:109], v[138:141], v[62:65]
	v_mfma_f32_16x16x32_f16 v[58:61], v[114:117], v[138:141], v[58:61]
	v_mfma_f32_16x16x32_f16 v[46:49], v[106:109], v[154:157], v[46:49]
	v_mfma_f32_16x16x32_f16 v[42:45], v[114:117], v[154:157], v[42:45]
	v_mfma_f32_16x16x32_f16 v[28:31], v[106:109], v[162:165], v[28:31]
	v_mfma_f32_16x16x32_f16 v[24:27], v[114:117], v[162:165], v[24:27]
	v_mfma_f32_16x16x32_f16 v[12:15], v[106:109], v[170:173], v[12:15]
	v_mfma_f32_16x16x32_f16 v[8:11], v[114:117], v[170:173], v[8:11]
	v_mfma_f32_16x16x32_f16 v[62:65], v[110:113], v[150:153], v[62:65]
	v_mfma_f32_16x16x32_f16 v[58:61], v[134:137], v[150:153], v[58:61]
	v_mfma_f32_16x16x32_f16 v[46:49], v[110:113], v[158:161], v[46:49]
	v_mfma_f32_16x16x32_f16 v[42:45], v[134:137], v[158:161], v[42:45]
	v_mfma_f32_16x16x32_f16 v[28:31], v[110:113], v[166:169], v[28:31]
	v_mfma_f32_16x16x32_f16 v[24:27], v[134:137], v[166:169], v[24:27]
	v_mfma_f32_16x16x32_f16 v[12:15], v[110:113], v[174:177], v[12:15]
	v_mfma_f32_16x16x32_f16 v[8:11], v[134:137], v[174:177], v[8:11]
	s_setprio 0
	s_barrier
	s_add_u32 s10, s14, 0xb0000
	s_addc_u32 s11, s15, 0
	s_add_i32 s47, s48, s23
	v_lshl_add_u64 v[106:107], s[10:11], 0, v[32:33]
	s_mov_b32 m0, s47
	s_nop 0
	global_load_lds_dwordx4 v[106:107], off
	v_lshl_add_u64 v[106:107], s[10:11], 0, v[182:183]
	s_add_i32 m0, s47, 0x2000
	s_nop 0
	global_load_lds_dwordx4 v[106:107], off
	s_waitcnt vmcnt(6)
	s_barrier
	s_setprio 1
	v_mfma_f32_16x16x32_f16 v[54:57], v[178:181], v[138:141], v[54:57]
	v_mfma_f32_16x16x32_f16 v[50:53], v[192:195], v[138:141], v[50:53]
	v_mfma_f32_16x16x32_f16 v[38:41], v[178:181], v[154:157], v[38:41]
	v_mfma_f32_16x16x32_f16 v[34:37], v[192:195], v[154:157], v[34:37]
	v_mfma_f32_16x16x32_f16 v[20:23], v[178:181], v[162:165], v[20:23]
	v_mfma_f32_16x16x32_f16 v[16:19], v[192:195], v[162:165], v[16:19]
	v_mfma_f32_16x16x32_f16 v[4:7], v[178:181], v[170:173], v[4:7]
	v_mfma_f32_16x16x32_f16 v[0:3], v[192:195], v[170:173], v[0:3]
	v_mfma_f32_16x16x32_f16 v[54:57], v[188:191], v[150:153], v[54:57]
	v_mfma_f32_16x16x32_f16 v[50:53], v[196:199], v[150:153], v[50:53]
	v_mfma_f32_16x16x32_f16 v[38:41], v[188:191], v[158:161], v[38:41]
	v_mfma_f32_16x16x32_f16 v[34:37], v[196:199], v[158:161], v[34:37]
	v_mfma_f32_16x16x32_f16 v[20:23], v[188:191], v[166:169], v[20:23]
	v_mfma_f32_16x16x32_f16 v[16:19], v[196:199], v[166:169], v[16:19]
	v_mfma_f32_16x16x32_f16 v[4:7], v[188:191], v[174:177], v[4:7]
	v_mfma_f32_16x16x32_f16 v[0:3], v[196:199], v[174:177], v[0:3]
	s_setprio 0
	s_add_i32 s47, 0, 0x18000
	v_add_u32_e32 v134, s47, v230
	s_barrier
	ds_read_b128 v[106:109], v134
	ds_read_b128 v[110:113], v134 offset:1024
	ds_read_b128 v[114:117], v134 offset:2048
	ds_read_b128 v[134:137], v134 offset:3072
	s_add_u32 s10, s16, 0xb0000
	s_addc_u32 s11, s17, 0
	s_mov_b32 m0, s26
	v_lshl_add_u64 v[178:179], s[10:11], 0, v[32:33]
	ds_read_b128 v[138:141], v232 offset:32768
	ds_read_b128 v[150:153], v232 offset:33792
	ds_read_b128 v[154:157], v232 offset:34816
	ds_read_b128 v[158:161], v232 offset:35840
	ds_read_b128 v[162:165], v232 offset:36864
	ds_read_b128 v[166:169], v232 offset:37888
	ds_read_b128 v[170:173], v232 offset:38912
	ds_read_b128 v[174:177], v232 offset:39936
	global_load_lds_dwordx4 v[178:179], off
	v_lshl_add_u64 v[178:179], s[10:11], 0, v[182:183]
	s_mov_b32 m0, s27
	s_nop 0
	global_load_lds_dwordx4 v[178:179], off
	s_waitcnt lgkmcnt(8)
	s_barrier
	s_waitcnt lgkmcnt(0)
	s_setprio 1
	s_waitcnt lgkmcnt(0)
	v_mfma_f32_16x16x32_f16 v[146:149], v[106:109], v[138:141], v[146:149]
	v_mfma_f32_16x16x32_f16 v[142:145], v[114:117], v[138:141], v[142:145]
	v_mfma_f32_16x16x32_f16 v[130:133], v[106:109], v[154:157], v[130:133]
	v_mfma_f32_16x16x32_f16 v[122:125], v[114:117], v[154:157], v[122:125]
	v_mfma_f32_16x16x32_f16 v[94:97], v[106:109], v[162:165], v[94:97]
	v_mfma_f32_16x16x32_f16 v[90:93], v[114:117], v[162:165], v[90:93]
	v_mfma_f32_16x16x32_f16 v[78:81], v[106:109], v[170:173], v[78:81]
	v_mfma_f32_16x16x32_f16 v[74:77], v[114:117], v[170:173], v[74:77]
	v_mfma_f32_16x16x32_f16 v[146:149], v[110:113], v[150:153], v[146:149]
	v_mfma_f32_16x16x32_f16 v[142:145], v[134:137], v[150:153], v[142:145]
	v_mfma_f32_16x16x32_f16 v[130:133], v[110:113], v[158:161], v[130:133]
	v_mfma_f32_16x16x32_f16 v[122:125], v[134:137], v[158:161], v[122:125]
	v_mfma_f32_16x16x32_f16 v[94:97], v[110:113], v[166:169], v[94:97]
	v_mfma_f32_16x16x32_f16 v[90:93], v[134:137], v[166:169], v[90:93]
	v_mfma_f32_16x16x32_f16 v[78:81], v[110:113], v[174:177], v[78:81]
	v_mfma_f32_16x16x32_f16 v[74:77], v[134:137], v[174:177], v[74:77]
	s_setprio 0
	s_barrier
	s_add_i32 s16, 0, 0x1c000
	s_add_i32 s10, s47, s23
	v_add_u32_e32 v196, s16, v230
	v_lshl_add_u64 v[200:201], v[200:201], 0, s[84:85]
	s_mov_b32 m0, s10
	ds_read_b128 v[178:181], v196
	ds_read_b128 v[188:191], v196 offset:1024
	ds_read_b128 v[192:195], v196 offset:2048
	ds_read_b128 v[196:199], v196 offset:3072
	global_load_lds_dwordx4 v[200:201], off
	v_lshl_add_u64 v[200:201], v[202:203], 0, s[84:85]
	s_add_i32 m0, s10, 0x2000
	s_nop 0
	global_load_lds_dwordx4 v[200:201], off
	s_barrier
	s_waitcnt lgkmcnt(0)
	s_setprio 1
	s_waitcnt lgkmcnt(0)
	v_mfma_f32_16x16x32_f16 v[126:129], v[178:181], v[138:141], v[126:129]
	v_mfma_f32_16x16x32_f16 v[118:121], v[192:195], v[138:141], v[118:121]
	v_mfma_f32_16x16x32_f16 v[102:105], v[178:181], v[154:157], v[102:105]
	v_mfma_f32_16x16x32_f16 v[98:101], v[192:195], v[154:157], v[98:101]
	v_mfma_f32_16x16x32_f16 v[86:89], v[178:181], v[162:165], v[86:89]
	v_mfma_f32_16x16x32_f16 v[82:85], v[192:195], v[162:165], v[82:85]
	v_mfma_f32_16x16x32_f16 v[70:73], v[178:181], v[170:173], v[70:73]
	v_mfma_f32_16x16x32_f16 v[66:69], v[192:195], v[170:173], v[66:69]
	v_mfma_f32_16x16x32_f16 v[126:129], v[188:191], v[150:153], v[126:129]
	v_mfma_f32_16x16x32_f16 v[118:121], v[196:199], v[150:153], v[118:121]
	v_mfma_f32_16x16x32_f16 v[102:105], v[188:191], v[158:161], v[102:105]
	v_mfma_f32_16x16x32_f16 v[98:101], v[196:199], v[158:161], v[98:101]
	v_mfma_f32_16x16x32_f16 v[86:89], v[188:191], v[166:169], v[86:89]
	v_mfma_f32_16x16x32_f16 v[82:85], v[196:199], v[166:169], v[82:85]
	v_mfma_f32_16x16x32_f16 v[70:73], v[188:191], v[174:177], v[70:73]
	v_mfma_f32_16x16x32_f16 v[66:69], v[196:199], v[174:177], v[66:69]
	s_setprio 0
	s_mov_b32 m0, s29
	v_lshl_add_u64 v[200:201], v[204:205], 0, s[84:85]
	s_barrier
	ds_read_b128 v[138:141], v232 offset:49152
	ds_read_b128 v[150:153], v232 offset:50176
	ds_read_b128 v[154:157], v232 offset:51200
	ds_read_b128 v[158:161], v232 offset:52224
	ds_read_b128 v[162:165], v232 offset:53248
	ds_read_b128 v[166:169], v232 offset:54272
	ds_read_b128 v[170:173], v232 offset:55296
	ds_read_b128 v[174:177], v232 offset:56320
	global_load_lds_dwordx4 v[200:201], off
	v_lshl_add_u64 v[200:201], v[206:207], 0, s[84:85]
	s_mov_b32 m0, s30
	s_nop 0
	global_load_lds_dwordx4 v[200:201], off
	s_barrier
	s_waitcnt lgkmcnt(0)
	s_setprio 1
	s_waitcnt lgkmcnt(0)
	v_mfma_f32_16x16x32_f16 v[62:65], v[106:109], v[138:141], v[62:65]
	v_mfma_f32_16x16x32_f16 v[58:61], v[114:117], v[138:141], v[58:61]
	v_mfma_f32_16x16x32_f16 v[46:49], v[106:109], v[154:157], v[46:49]
	v_mfma_f32_16x16x32_f16 v[42:45], v[114:117], v[154:157], v[42:45]
	v_mfma_f32_16x16x32_f16 v[28:31], v[106:109], v[162:165], v[28:31]
	v_mfma_f32_16x16x32_f16 v[24:27], v[114:117], v[162:165], v[24:27]
	v_mfma_f32_16x16x32_f16 v[12:15], v[106:109], v[170:173], v[12:15]
	v_mfma_f32_16x16x32_f16 v[8:11], v[114:117], v[170:173], v[8:11]
	v_mfma_f32_16x16x32_f16 v[62:65], v[110:113], v[150:153], v[62:65]
	v_mfma_f32_16x16x32_f16 v[58:61], v[134:137], v[150:153], v[58:61]
	v_mfma_f32_16x16x32_f16 v[46:49], v[110:113], v[158:161], v[46:49]
	v_mfma_f32_16x16x32_f16 v[42:45], v[134:137], v[158:161], v[42:45]
	v_mfma_f32_16x16x32_f16 v[28:31], v[110:113], v[166:169], v[28:31]
	v_mfma_f32_16x16x32_f16 v[24:27], v[134:137], v[166:169], v[24:27]
	v_mfma_f32_16x16x32_f16 v[12:15], v[110:113], v[174:177], v[12:15]
	v_mfma_f32_16x16x32_f16 v[8:11], v[134:137], v[174:177], v[8:11]
	s_setprio 0
	s_barrier
	s_add_u32 s10, s14, 0xb0080
	s_addc_u32 s11, s15, 0
	s_add_i32 s14, s16, s23
	v_lshl_add_u64 v[106:107], s[10:11], 0, v[32:33]
	s_mov_b32 m0, s14
	s_nop 0
	global_load_lds_dwordx4 v[106:107], off
	v_lshl_add_u64 v[106:107], s[10:11], 0, v[182:183]
	s_add_i32 m0, s14, 0x2000
	s_nop 0
	global_load_lds_dwordx4 v[106:107], off
	s_waitcnt vmcnt(6)
	s_barrier
	s_setprio 1
	v_mfma_f32_16x16x32_f16 v[54:57], v[178:181], v[138:141], v[54:57]
	v_mfma_f32_16x16x32_f16 v[50:53], v[192:195], v[138:141], v[50:53]
	v_mfma_f32_16x16x32_f16 v[38:41], v[178:181], v[154:157], v[38:41]
	v_mfma_f32_16x16x32_f16 v[34:37], v[192:195], v[154:157], v[34:37]
	v_mfma_f32_16x16x32_f16 v[20:23], v[178:181], v[162:165], v[20:23]
	v_mfma_f32_16x16x32_f16 v[16:19], v[192:195], v[162:165], v[16:19]
	v_mfma_f32_16x16x32_f16 v[4:7], v[178:181], v[170:173], v[4:7]
	v_mfma_f32_16x16x32_f16 v[0:3], v[192:195], v[170:173], v[0:3]
	v_mfma_f32_16x16x32_f16 v[54:57], v[188:191], v[150:153], v[54:57]
	v_mfma_f32_16x16x32_f16 v[50:53], v[196:199], v[150:153], v[50:53]
	v_mfma_f32_16x16x32_f16 v[38:41], v[188:191], v[158:161], v[38:41]
	v_mfma_f32_16x16x32_f16 v[34:37], v[196:199], v[158:161], v[34:37]
	v_mfma_f32_16x16x32_f16 v[20:23], v[188:191], v[166:169], v[20:23]
	v_mfma_f32_16x16x32_f16 v[16:19], v[196:199], v[166:169], v[16:19]
	v_mfma_f32_16x16x32_f16 v[4:7], v[188:191], v[174:177], v[4:7]
	v_mfma_f32_16x16x32_f16 v[0:3], v[196:199], v[174:177], v[0:3]
	s_setprio 0
	s_add_u32 s44, s44, 0x100
	s_addc_u32 s45, s45, 0
	s_cmp_ge_u32 s46, s42
	s_mov_b64 s[10:11], s[12:13]
	s_mov_b32 s14, s46
	s_barrier
	s_cbranch_scc0 .LBB0_1365
	s_cmp_eq_u32 s40, 0
	s_cselect_b32 s6, 0x9000, 0
	v_lshl_or_b32 v106, s41, 8, v231
	s_add_u32 s6, s31, s6
	s_addc_u32 s7, s34, 0
	v_ashrrev_i32_e32 v107, 31, v106
	v_lshl_add_u64 v[116:117], v[106:107], 2, s[6:7]
	global_load_dwordx4 v[108:111], v[116:117], off offset:16
	global_load_dwordx4 v[112:115], v[116:117], off
	s_cmp_eq_u32 s39, 0
	s_waitcnt vmcnt(0)
	v_pk_mul_f32 v[194:195], v[110:111], 0.5 op_sel_hi:[1,0]
	v_pk_mul_f32 v[198:199], v[114:115], 0.5 op_sel_hi:[1,0]
	v_pk_mul_f32 v[202:203], v[112:113], 0.5 op_sel_hi:[1,0]
	v_pk_mul_f32 v[200:201], v[108:109], 0.5 op_sel_hi:[1,0]
	global_load_dwordx4 v[108:111], v[116:117], off offset:528
	global_load_dwordx4 v[112:115], v[116:117], off offset:512
	s_waitcnt vmcnt(0)
	v_pk_mul_f32 v[188:189], v[110:111], 0.5 op_sel_hi:[1,0]
	v_pk_mul_f32 v[196:197], v[112:113], 0.5 op_sel_hi:[1,0]
	v_lshl_add_u32 v112, s40, 8, v229
	v_pk_mul_f32 v[190:191], v[114:115], 0.5 op_sel_hi:[1,0]
	v_pk_mul_f32 v[192:193], v[108:109], 0.5 op_sel_hi:[1,0]
	v_or_b32_e32 v114, 16, v112
	v_or_b32_e32 v110, 32, v112
	v_or_b32_e32 v108, 48, v112
	v_ashrrev_i32_e32 v113, 31, v112
	v_ashrrev_i32_e32 v115, 31, v114
	v_ashrrev_i32_e32 v111, 31, v110
	v_ashrrev_i32_e32 v109, 31, v108
	s_cbranch_scc1 .LBB0_1368
	s_add_i32 s96, s39, -1
	s_lshl_b64 s[6:7], s[96:97], 20
	v_readlane_b32 s8, v252, 11
	v_readlane_b32 s9, v252, 12
	s_add_u32 s6, s8, s6
	s_addc_u32 s7, s9, s7
	v_lshlrev_b64 v[138:139], 2, v[106:107]
	v_lshrrev_b32_e32 v150, 5, v220
	v_mul_u32_u24_e32 v150, 48, v150
	s_nop 0
	v_sub_co_u32_e32 v138, vcc, v138, v150
	s_nop 1
	v_subbrev_co_u32_e32 v139, vcc, 0, v139, vcc
	v_lshl_add_u64 v[138:139], s[6:7], 0, v[138:139]
	s_mov_b64 s[6:7], 0x80000
	v_lshlrev_b64 v[204:205], 12, v[112:113]
	v_lshl_add_u64 v[204:205], v[204:205], 0, v[138:139]
	v_lshl_add_u64 v[212:213], v[204:205], 0, s[6:7]
	v_lshlrev_b64 v[206:207], 12, v[114:115]
	v_lshl_add_u64 v[206:207], v[206:207], 0, v[138:139]
	v_lshl_add_u64 v[214:215], v[206:207], 0, s[6:7]
	v_lshlrev_b64 v[208:209], 12, v[110:111]
	v_lshl_add_u64 v[208:209], v[208:209], 0, v[138:139]
	v_lshl_add_u64 v[216:217], v[208:209], 0, s[6:7]
	v_lshlrev_b64 v[210:211], 12, v[108:109]
	v_lshl_add_u64 v[210:211], v[210:211], 0, v[138:139]
	v_lshl_add_u64 v[218:219], v[210:211], 0, s[6:7]
	v_pk_mul_f32 v[152:153], v[146:147], v[202:203]
	v_pk_mul_f32 v[154:155], v[148:149], v[198:199]
	v_pk_mul_f32 v[156:157], v[142:143], v[200:201]
	v_pk_mul_f32 v[158:159], v[144:145], v[194:195]
	s_nop 1
	v_permlane32_swap_b32_e32 v152, v156
	v_permlane32_swap_b32_e32 v153, v157
	v_permlane32_swap_b32_e32 v154, v158
	v_permlane32_swap_b32_e32 v155, v159
	s_nop 0
	global_store_dwordx4 v[204:205], v[152:155], off
	global_store_dwordx4 v[204:205], v[156:159], off offset:64
	v_pk_mul_f32 v[160:161], v[126:127], v[196:197]
	v_pk_mul_f32 v[162:163], v[128:129], v[190:191]
	v_pk_mul_f32 v[164:165], v[118:119], v[192:193]
	v_pk_mul_f32 v[166:167], v[120:121], v[188:189]
	s_nop 1
	v_permlane32_swap_b32_e32 v160, v164
	v_permlane32_swap_b32_e32 v161, v165
	v_permlane32_swap_b32_e32 v162, v166
	v_permlane32_swap_b32_e32 v163, v167
	s_nop 0
	global_store_dwordx4 v[204:205], v[160:163], off offset:512
	global_store_dwordx4 v[204:205], v[164:167], off offset:576
	v_pk_mul_f32 v[168:169], v[130:131], v[202:203]
	v_pk_mul_f32 v[170:171], v[132:133], v[198:199]
	v_pk_mul_f32 v[172:173], v[122:123], v[200:201]
	v_pk_mul_f32 v[174:175], v[124:125], v[194:195]
	s_nop 1
	v_permlane32_swap_b32_e32 v168, v172
	v_permlane32_swap_b32_e32 v169, v173
	v_permlane32_swap_b32_e32 v170, v174
	v_permlane32_swap_b32_e32 v171, v175
	s_nop 0
	global_store_dwordx4 v[206:207], v[168:171], off
	global_store_dwordx4 v[206:207], v[172:175], off offset:64
	v_pk_mul_f32 v[176:177], v[102:103], v[196:197]
	v_pk_mul_f32 v[178:179], v[104:105], v[190:191]
	v_pk_mul_f32 v[180:181], v[98:99], v[192:193]
	v_pk_mul_f32 v[182:183], v[100:101], v[188:189]
	s_nop 1
	v_permlane32_swap_b32_e32 v176, v180
	v_permlane32_swap_b32_e32 v177, v181
	v_permlane32_swap_b32_e32 v178, v182
	v_permlane32_swap_b32_e32 v179, v183
	s_nop 0
	global_store_dwordx4 v[206:207], v[176:179], off offset:512
	global_store_dwordx4 v[206:207], v[180:183], off offset:576
	v_pk_mul_f32 v[152:153], v[94:95], v[202:203]
	v_pk_mul_f32 v[154:155], v[96:97], v[198:199]
	v_pk_mul_f32 v[156:157], v[90:91], v[200:201]
	v_pk_mul_f32 v[158:159], v[92:93], v[194:195]
	s_nop 1
	v_permlane32_swap_b32_e32 v152, v156
	v_permlane32_swap_b32_e32 v153, v157
	v_permlane32_swap_b32_e32 v154, v158
	v_permlane32_swap_b32_e32 v155, v159
	s_nop 0
	global_store_dwordx4 v[208:209], v[152:155], off
	global_store_dwordx4 v[208:209], v[156:159], off offset:64
	v_pk_mul_f32 v[160:161], v[86:87], v[196:197]
	v_pk_mul_f32 v[162:163], v[88:89], v[190:191]
	v_pk_mul_f32 v[164:165], v[82:83], v[192:193]
	v_pk_mul_f32 v[166:167], v[84:85], v[188:189]
	s_nop 1
	v_permlane32_swap_b32_e32 v160, v164
	v_permlane32_swap_b32_e32 v161, v165
	v_permlane32_swap_b32_e32 v162, v166
	v_permlane32_swap_b32_e32 v163, v167
	s_nop 0
	global_store_dwordx4 v[208:209], v[160:163], off offset:512
	global_store_dwordx4 v[208:209], v[164:167], off offset:576
	v_pk_mul_f32 v[168:169], v[78:79], v[202:203]
	v_pk_mul_f32 v[170:171], v[80:81], v[198:199]
	v_pk_mul_f32 v[172:173], v[74:75], v[200:201]
	v_pk_mul_f32 v[174:175], v[76:77], v[194:195]
	s_nop 1
	v_permlane32_swap_b32_e32 v168, v172
	v_permlane32_swap_b32_e32 v169, v173
	v_permlane32_swap_b32_e32 v170, v174
	v_permlane32_swap_b32_e32 v171, v175
	s_nop 0
	global_store_dwordx4 v[210:211], v[168:171], off
	global_store_dwordx4 v[210:211], v[172:175], off offset:64
	v_pk_mul_f32 v[176:177], v[70:71], v[196:197]
	v_pk_mul_f32 v[178:179], v[72:73], v[190:191]
	v_pk_mul_f32 v[180:181], v[66:67], v[192:193]
	v_pk_mul_f32 v[182:183], v[68:69], v[188:189]
	s_nop 1
	v_permlane32_swap_b32_e32 v176, v180
	v_permlane32_swap_b32_e32 v177, v181
	v_permlane32_swap_b32_e32 v178, v182
	v_permlane32_swap_b32_e32 v179, v183
	s_nop 0
	global_store_dwordx4 v[210:211], v[176:179], off offset:512
	global_store_dwordx4 v[210:211], v[180:183], off offset:576
	v_pk_mul_f32 v[152:153], v[62:63], v[202:203]
	v_pk_mul_f32 v[154:155], v[64:65], v[198:199]
	v_pk_mul_f32 v[156:157], v[58:59], v[200:201]
	v_pk_mul_f32 v[158:159], v[60:61], v[194:195]
	s_nop 1
	v_permlane32_swap_b32_e32 v152, v156
	v_permlane32_swap_b32_e32 v153, v157
	v_permlane32_swap_b32_e32 v154, v158
	v_permlane32_swap_b32_e32 v155, v159
	s_nop 0
	global_store_dwordx4 v[212:213], v[152:155], off
	global_store_dwordx4 v[212:213], v[156:159], off offset:64
	v_pk_mul_f32 v[160:161], v[54:55], v[196:197]
	v_pk_mul_f32 v[162:163], v[56:57], v[190:191]
	v_pk_mul_f32 v[164:165], v[50:51], v[192:193]
	v_pk_mul_f32 v[166:167], v[52:53], v[188:189]
	s_nop 1
	v_permlane32_swap_b32_e32 v160, v164
	v_permlane32_swap_b32_e32 v161, v165
	v_permlane32_swap_b32_e32 v162, v166
	v_permlane32_swap_b32_e32 v163, v167
	s_nop 0
	global_store_dwordx4 v[212:213], v[160:163], off offset:512
	global_store_dwordx4 v[212:213], v[164:167], off offset:576
	v_pk_mul_f32 v[168:169], v[46:47], v[202:203]
	v_pk_mul_f32 v[170:171], v[48:49], v[198:199]
	v_pk_mul_f32 v[172:173], v[42:43], v[200:201]
	v_pk_mul_f32 v[174:175], v[44:45], v[194:195]
	s_nop 1
	v_permlane32_swap_b32_e32 v168, v172
	v_permlane32_swap_b32_e32 v169, v173
	v_permlane32_swap_b32_e32 v170, v174
	v_permlane32_swap_b32_e32 v171, v175
	s_nop 0
	global_store_dwordx4 v[214:215], v[168:171], off
	global_store_dwordx4 v[214:215], v[172:175], off offset:64
	v_pk_mul_f32 v[176:177], v[38:39], v[196:197]
	v_pk_mul_f32 v[178:179], v[40:41], v[190:191]
	v_pk_mul_f32 v[180:181], v[34:35], v[192:193]
	v_pk_mul_f32 v[182:183], v[36:37], v[188:189]
	s_nop 1
	v_permlane32_swap_b32_e32 v176, v180
	v_permlane32_swap_b32_e32 v177, v181
	v_permlane32_swap_b32_e32 v178, v182
	v_permlane32_swap_b32_e32 v179, v183
	s_nop 0
	global_store_dwordx4 v[214:215], v[176:179], off offset:512
	global_store_dwordx4 v[214:215], v[180:183], off offset:576
	v_pk_mul_f32 v[152:153], v[28:29], v[202:203]
	v_pk_mul_f32 v[154:155], v[30:31], v[198:199]
	v_pk_mul_f32 v[156:157], v[24:25], v[200:201]
	v_pk_mul_f32 v[158:159], v[26:27], v[194:195]
	s_nop 1
	v_permlane32_swap_b32_e32 v152, v156
	v_permlane32_swap_b32_e32 v153, v157
	v_permlane32_swap_b32_e32 v154, v158
	v_permlane32_swap_b32_e32 v155, v159
	s_nop 0
	global_store_dwordx4 v[216:217], v[152:155], off
	global_store_dwordx4 v[216:217], v[156:159], off offset:64
	v_pk_mul_f32 v[160:161], v[20:21], v[196:197]
	v_pk_mul_f32 v[162:163], v[22:23], v[190:191]
	v_pk_mul_f32 v[164:165], v[16:17], v[192:193]
	v_pk_mul_f32 v[166:167], v[18:19], v[188:189]
	s_nop 1
	v_permlane32_swap_b32_e32 v160, v164
	v_permlane32_swap_b32_e32 v161, v165
	v_permlane32_swap_b32_e32 v162, v166
	v_permlane32_swap_b32_e32 v163, v167
	s_nop 0
	global_store_dwordx4 v[216:217], v[160:163], off offset:512
	global_store_dwordx4 v[216:217], v[164:167], off offset:576
	v_pk_mul_f32 v[168:169], v[12:13], v[202:203]
	v_pk_mul_f32 v[170:171], v[14:15], v[198:199]
	v_pk_mul_f32 v[172:173], v[8:9], v[200:201]
	v_pk_mul_f32 v[174:175], v[10:11], v[194:195]
	s_nop 1
	v_permlane32_swap_b32_e32 v168, v172
	v_permlane32_swap_b32_e32 v169, v173
	v_permlane32_swap_b32_e32 v170, v174
	v_permlane32_swap_b32_e32 v171, v175
	s_nop 0
	global_store_dwordx4 v[218:219], v[168:171], off
	global_store_dwordx4 v[218:219], v[172:175], off offset:64
	v_pk_mul_f32 v[176:177], v[4:5], v[196:197]
	v_pk_mul_f32 v[178:179], v[6:7], v[190:191]
	v_pk_mul_f32 v[180:181], v[0:1], v[192:193]
	v_pk_mul_f32 v[182:183], v[2:3], v[188:189]
	s_nop 1
	v_permlane32_swap_b32_e32 v176, v180
	v_permlane32_swap_b32_e32 v177, v181
	v_permlane32_swap_b32_e32 v178, v182
	v_permlane32_swap_b32_e32 v179, v183
	s_nop 0
	global_store_dwordx4 v[218:219], v[176:179], off offset:512
	global_store_dwordx4 v[218:219], v[180:183], off offset:576
	s_cbranch_execnz .LBB0_1352
	s_branch .LBB0_1351
